# GEMM tile boundary: align / re-stagger barriers skipped for plain-epilogue tiles that have a next tile (stagger kept across tiles)
# speedup vs baseline: 1.0006x; 1.0006x over previous
; #define PG8_BAR __builtin_amdgcn_s_barrier()
; __device__ __forceinline__ void gemm_phase(LAS unsigned char* lds, const Gemm g, const StaticOrder& S, const Epi& E, const int tid) {
;     ...
;         if (wr == 0) PG8_BAR;
;         if (E.mode == 2) E.ffn(acc, cur, wr, wc, fr, fq, lane); else E(acc, cur, wr, wc, fr, fq);
.LBB0_531:
	s_and_b64 vcc, exec, s[16:17]
	s_cbranch_vccz .LBB0_533
	v_readlane_b32 s4, v255, 0
	v_readlane_b32 s5, v255, 1
	s_nop 0
	s_andn2_b64 s[4:5], s[4:5], s[58:59]
	s_and_b64 vcc, exec, s[4:5]
	s_cbranch_vccnz .LBB0_533
	s_barrier

; #define PG8_BAR __builtin_amdgcn_s_barrier()
; __device__ __forceinline__ void gemm_phase(LAS unsigned char* lds, const Gemm g, const StaticOrder& S, const Epi& E, const int tid) {
;     ...
;         cur = nxt; cA = nA; cB = nB; ++ui;
;         if (wr == 1) PG8_BAR;
;     }
.LBB0_597:
	v_readlane_b32 s2, v254, 42
	v_readlane_b32 s3, v254, 43
	s_andn2_b64 vcc, exec, s[2:3]
	s_cbranch_vccnz .LBB0_512
	v_readlane_b32 s2, v255, 0
	v_readlane_b32 s3, v255, 1
	s_nop 0
	s_and_b64 vcc, exec, s[2:3]
	s_cbranch_vccnz .LBB0_512
	s_barrier
	s_branch .LBB0_512
